# all three big GEMM K-loops (z, w_out, w_ple_gate): LDS-DMA loads with scalar base + 32-bit lane offset instead of a 64-bit VALU add per load
# speedup vs baseline: 1.0135x; 1.0007x over previous
; #define PG8_STAGE(bufoff, gbase, voff) do { unsigned long long _gb = (unsigned long long)(gbase); asm volatile("" : "+s"(_gb)); _Pragma("unroll") for (int _i = 0; _i < 2; ++_i) \
;         __builtin_amdgcn_global_load_lds((const GAS unsigned*)((const GAS char*)_gb + (voff)[_i]), (LAS unsigned*)(lds + (bufoff) + ldsw + _i * 8192), 16, 0, 0); } while (0)
; #define PG8_LDA(dst, b, h) do { _Pragma("unroll") for (int m = 0; m < 4; ++m) _Pragma("unroll") for (int k = 0; k < 2; ++k) dst[m][k] = *(const LAS bf16x8*)(lds + PG8_SA(b, h) + aoff + m * 2048 + k * 1024); } while (0)
; #define PG8_LDB(dst, b, h) do { _Pragma("unroll") for (int n = 0; n < 2; ++n) _Pragma("unroll") for (int k = 0; k < 2; ++k) dst[n][k] = *(const LAS bf16x8*)(lds + PG8_SB(b, h) + boff + n * 2048 + k * 1024); } while (0)
; #define PG8_MMA(ai, bj, At, Bt) do { __builtin_amdgcn_s_setprio(1); _Pragma("unroll") for (int m = 0; m < 4; ++m) _Pragma("unroll") for (int n = 0; n < 2; ++n) _Pragma("unroll") for (int k = 0; k < 2; ++k) \
;         acc[ai][bj][m][n] = __builtin_amdgcn_mfma_f32_16x16x32_bf16(Bt[n][k], At[m][k], acc[ai][bj][m][n], 0, 0, 0); __builtin_amdgcn_s_setprio(0); } while (0)
; #define PG8_WAIT_V(n) asm volatile("s_waitcnt vmcnt(" #n ")" ::: "memory")
; #define PG8_WAIT_L(n) asm volatile("s_waitcnt lgkmcnt(" #n ")" ::: "memory")
; #define PG8_BAR __builtin_amdgcn_s_barrier()
; template <class Epi, bool ALIGN_EPI>
; __device__ __forceinline__ void gemm_phase(LAS unsigned char* lds, const Gemm g, const StaticOrder& S, const Epi& E, const int wid) {
;     ...
;             const bool last = (t == nt - 2);
;             const char* a1 = cA + (size_t)(t + 1) * kstep;
;             const char* a2 = last ? nA : cA + (size_t)(t + 2) * kstep; const char* b2 = last ? nB : cB + (size_t)(t + 2) * kstep;
;             const char* a3 = a2 + kstep; const char* b3 = b2 + kstep;
;             PG8_LDB(B0, 0, 0); PG8_LDB(B1, 0, 1); PG8_SCHED; PG8_LDA(At, 0, 0); PG8_STAGE(PG8_SA(1, 1), a1 + hstep, voffA);
;             PG8_WAIT_V(8); PG8_WAIT_L(0); PG8_BAR; PG8_MMA(0, 0, At, B0); PG8_MMA(0, 1, At, B1); PG8_BAR; PG8_SCHED;
;             PG8_LDA(At, 0, 1); PG8_STAGE(PG8_SB(0, 0), b2, voffB); PG8_STAGE(PG8_SB(0, 1), b2 + hstepB, voffB); PG8_STAGE(PG8_SA(0, 0), a2, voffA);
;             PG8_WAIT_V(8); PG8_WAIT_L(0); PG8_BAR; PG8_MMA(1, 0, At, B0); PG8_MMA(1, 1, At, B1); PG8_BAR; PG8_SCHED;
.LBB0_722:
	ds_read_b128 v[128:131], v203
	ds_read_b128 v[132:135], v203 offset:1024
	ds_read_b128 v[136:139], v203 offset:2048
	ds_read_b128 v[140:143], v203 offset:3072
	ds_read_b128 v[144:147], v204
	ds_read_b128 v[148:151], v204 offset:1024
	ds_read_b128 v[152:155], v204 offset:2048
	ds_read_b128 v[156:159], v204 offset:3072
	s_cmp_eq_u32 s52, 28
	s_cselect_b32 s30, s21, s50
	s_cselect_b32 s31, s15, s51
	s_cselect_b32 s28, s47, s48
	s_cselect_b32 s29, s13, s49
	s_add_u32 s26, s30, 0x80
	s_addc_u32 s27, s31, 0
	s_mov_b64 s[54:55], s[24:25]
	ds_read_b128 v[160:163], v205
	ds_read_b128 v[164:167], v205 offset:1024
	ds_read_b128 v[168:171], v205 offset:2048
	ds_read_b128 v[172:175], v205 offset:3072
	ds_read_b128 v[188:191], v205 offset:4096
	ds_read_b128 v[192:195], v205 offset:5120
	ds_read_b128 v[196:199], v205 offset:6144
	ds_read_b128 v[206:209], v205 offset:7168
	s_add_i32 m0, s23, 0xc000
	s_nop 0
	global_load_lds_dwordx4 v176, s[54:55]
	s_add_i32 m0, s23, 0xe000
	s_nop 0
	global_load_lds_dwordx4 v180, s[54:55]
	s_waitcnt vmcnt(8)
	s_waitcnt lgkmcnt(0)
	s_barrier
	s_setprio 1
	v_mfma_f32_16x16x32_bf16 v[124:127], v[128:131], v[160:163], v[124:127]
	v_mfma_f32_16x16x32_bf16 v[120:123], v[136:139], v[160:163], v[120:123]
	v_mfma_f32_16x16x32_bf16 v[108:111], v[128:131], v[168:171], v[108:111]
	v_mfma_f32_16x16x32_bf16 v[104:107], v[136:139], v[168:171], v[104:107]
	v_mfma_f32_16x16x32_bf16 v[92:95], v[128:131], v[188:191], v[92:95]
	v_mfma_f32_16x16x32_bf16 v[88:91], v[136:139], v[188:191], v[88:91]
	v_mfma_f32_16x16x32_bf16 v[76:79], v[128:131], v[196:199], v[76:79]
	v_mfma_f32_16x16x32_bf16 v[72:75], v[136:139], v[196:199], v[72:75]
	v_mfma_f32_16x16x32_bf16 v[124:127], v[132:135], v[164:167], v[124:127]
	v_mfma_f32_16x16x32_bf16 v[120:123], v[140:143], v[164:167], v[120:123]
	v_mfma_f32_16x16x32_bf16 v[108:111], v[132:135], v[172:175], v[108:111]
	v_mfma_f32_16x16x32_bf16 v[104:107], v[140:143], v[172:175], v[104:107]
	v_mfma_f32_16x16x32_bf16 v[92:95], v[132:135], v[192:195], v[92:95]
	v_mfma_f32_16x16x32_bf16 v[88:91], v[140:143], v[192:195], v[88:91]
	v_mfma_f32_16x16x32_bf16 v[76:79], v[132:135], v[206:209], v[76:79]
	v_mfma_f32_16x16x32_bf16 v[72:75], v[140:143], v[206:209], v[72:75]
	v_mfma_f32_16x16x32_bf16 v[116:119], v[144:147], v[160:163], v[116:119]
	v_mfma_f32_16x16x32_bf16 v[112:115], v[152:155], v[160:163], v[112:115]
	v_mfma_f32_16x16x32_bf16 v[100:103], v[144:147], v[168:171], v[100:103]
	v_mfma_f32_16x16x32_bf16 v[96:99], v[152:155], v[168:171], v[96:99]
	v_mfma_f32_16x16x32_bf16 v[84:87], v[144:147], v[188:191], v[84:87]
	v_mfma_f32_16x16x32_bf16 v[80:83], v[152:155], v[188:191], v[80:83]
	v_mfma_f32_16x16x32_bf16 v[68:71], v[144:147], v[196:199], v[68:71]
	v_mfma_f32_16x16x32_bf16 v[64:67], v[152:155], v[196:199], v[64:67]
	v_mfma_f32_16x16x32_bf16 v[116:119], v[148:151], v[164:167], v[116:119]
	v_mfma_f32_16x16x32_bf16 v[112:115], v[156:159], v[164:167], v[112:115]
	v_mfma_f32_16x16x32_bf16 v[100:103], v[148:151], v[172:175], v[100:103]
	v_mfma_f32_16x16x32_bf16 v[96:99], v[156:159], v[172:175], v[96:99]
	v_mfma_f32_16x16x32_bf16 v[84:87], v[148:151], v[192:195], v[84:87]
	v_mfma_f32_16x16x32_bf16 v[80:83], v[156:159], v[192:195], v[80:83]
	v_mfma_f32_16x16x32_bf16 v[68:71], v[148:151], v[206:209], v[68:71]
	v_mfma_f32_16x16x32_bf16 v[64:67], v[156:159], v[206:209], v[64:67]
	s_setprio 0
	s_barrier
	s_mov_b64 s[54:55], s[28:29]
	s_add_i32 s53, s45, s33
	ds_read_b128 v[160:163], v205 offset:16384
	ds_read_b128 v[164:167], v205 offset:17408
	ds_read_b128 v[168:171], v205 offset:18432
	ds_read_b128 v[172:175], v205 offset:19456
	ds_read_b128 v[188:191], v205 offset:20480
	ds_read_b128 v[192:195], v205 offset:21504
	ds_read_b128 v[196:199], v205 offset:22528
	ds_read_b128 v[206:209], v205 offset:23552
	s_mov_b32 m0, s53
	s_nop 0
	global_load_lds_dwordx4 v178, s[54:55]
	s_add_i32 m0, s53, 0x2000
	s_nop 0
	global_load_lds_dwordx4 v182, s[54:55]
	s_add_u32 s54, s28, 0x20000
	s_addc_u32 s55, s29, 0
	s_add_i32 s53, s46, s33
	s_mov_b32 m0, s53
	s_nop 0
	global_load_lds_dwordx4 v178, s[54:55]
	s_add_i32 m0, s53, 0x2000
	s_nop 0
	global_load_lds_dwordx4 v182, s[54:55]
	s_mov_b64 s[54:55], s[30:31]
	s_mov_b32 m0, s23
	s_nop 0
	global_load_lds_dwordx4 v176, s[54:55]
	s_mov_b32 m0, s38
	s_nop 0
	global_load_lds_dwordx4 v180, s[54:55]
	s_waitcnt vmcnt(8)
	s_waitcnt lgkmcnt(0)
	s_barrier
	s_setprio 1
	v_mfma_f32_16x16x32_bf16 v[60:63], v[128:131], v[160:163], v[60:63]
	v_mfma_f32_16x16x32_bf16 v[56:59], v[136:139], v[160:163], v[56:59]
	v_mfma_f32_16x16x32_bf16 v[44:47], v[128:131], v[168:171], v[44:47]
	v_mfma_f32_16x16x32_bf16 v[40:43], v[136:139], v[168:171], v[40:43]
	v_mfma_f32_16x16x32_bf16 v[28:31], v[128:131], v[188:191], v[28:31]
	v_mfma_f32_16x16x32_bf16 v[24:27], v[136:139], v[188:191], v[24:27]
	v_mfma_f32_16x16x32_bf16 v[12:15], v[128:131], v[196:199], v[12:15]
	v_mfma_f32_16x16x32_bf16 v[8:11], v[136:139], v[196:199], v[8:11]
	v_mfma_f32_16x16x32_bf16 v[60:63], v[132:135], v[164:167], v[60:63]
	v_mfma_f32_16x16x32_bf16 v[56:59], v[140:143], v[164:167], v[56:59]
	v_mfma_f32_16x16x32_bf16 v[44:47], v[132:135], v[172:175], v[44:47]
	v_mfma_f32_16x16x32_bf16 v[40:43], v[140:143], v[172:175], v[40:43]
	v_mfma_f32_16x16x32_bf16 v[28:31], v[132:135], v[192:195], v[28:31]
	v_mfma_f32_16x16x32_bf16 v[24:27], v[140:143], v[192:195], v[24:27]
	v_mfma_f32_16x16x32_bf16 v[12:15], v[132:135], v[206:209], v[12:15]
	v_mfma_f32_16x16x32_bf16 v[8:11], v[140:143], v[206:209], v[8:11]
	v_mfma_f32_16x16x32_bf16 v[52:55], v[144:147], v[160:163], v[52:55]
	v_mfma_f32_16x16x32_bf16 v[48:51], v[152:155], v[160:163], v[48:51]
	v_mfma_f32_16x16x32_bf16 v[36:39], v[144:147], v[168:171], v[36:39]
	v_mfma_f32_16x16x32_bf16 v[32:35], v[152:155], v[168:171], v[32:35]
	v_mfma_f32_16x16x32_bf16 v[20:23], v[144:147], v[188:191], v[20:23]
	v_mfma_f32_16x16x32_bf16 v[16:19], v[152:155], v[188:191], v[16:19]
	v_mfma_f32_16x16x32_bf16 v[4:7], v[144:147], v[196:199], v[4:7]
	v_mfma_f32_16x16x32_bf16 v[0:3], v[152:155], v[196:199], v[0:3]
	v_mfma_f32_16x16x32_bf16 v[52:55], v[148:151], v[164:167], v[52:55]
	v_mfma_f32_16x16x32_bf16 v[48:51], v[156:159], v[164:167], v[48:51]
	v_mfma_f32_16x16x32_bf16 v[36:39], v[148:151], v[172:175], v[36:39]
	v_mfma_f32_16x16x32_bf16 v[32:35], v[156:159], v[172:175], v[32:35]
	v_mfma_f32_16x16x32_bf16 v[20:23], v[148:151], v[192:195], v[20:23]
	v_mfma_f32_16x16x32_bf16 v[16:19], v[156:159], v[192:195], v[16:19]
	v_mfma_f32_16x16x32_bf16 v[4:7], v[148:151], v[206:209], v[4:7]
	v_mfma_f32_16x16x32_bf16 v[0:3], v[156:159], v[206:209], v[0:3]
	s_setprio 0
	s_barrier
; #define PG8_STAGE(bufoff, gbase, voff) do { unsigned long long _gb = (unsigned long long)(gbase); asm volatile("" : "+s"(_gb)); _Pragma("unroll") for (int _i = 0; _i < 2; ++_i) \
;         __builtin_amdgcn_global_load_lds((const GAS unsigned*)((const GAS char*)_gb + (voff)[_i]), (LAS unsigned*)(lds + (bufoff) + ldsw + _i * 8192), 16, 0, 0); } while (0)
; #define PG8_LDA(dst, b, h) do { _Pragma("unroll") for (int m = 0; m < 4; ++m) _Pragma("unroll") for (int k = 0; k < 2; ++k) dst[m][k] = *(const LAS bf16x8*)(lds + PG8_SA(b, h) + aoff + m * 2048 + k * 1024); } while (0)
; #define PG8_LDB(dst, b, h) do { _Pragma("unroll") for (int n = 0; n < 2; ++n) _Pragma("unroll") for (int k = 0; k < 2; ++k) dst[n][k] = *(const LAS bf16x8*)(lds + PG8_SB(b, h) + boff + n * 2048 + k * 1024); } while (0)
; #define PG8_MMA(ai, bj, At, Bt) do { __builtin_amdgcn_s_setprio(1); _Pragma("unroll") for (int m = 0; m < 4; ++m) _Pragma("unroll") for (int n = 0; n < 2; ++n) _Pragma("unroll") for (int k = 0; k < 2; ++k) \
;         acc[ai][bj][m][n] = __builtin_amdgcn_mfma_f32_16x16x32_bf16(Bt[n][k], At[m][k], acc[ai][bj][m][n], 0, 0, 0); __builtin_amdgcn_s_setprio(0); } while (0)
; #define PG8_WAIT_V(n) asm volatile("s_waitcnt vmcnt(" #n ")" ::: "memory")
; #define PG8_WAIT_L(n) asm volatile("s_waitcnt lgkmcnt(" #n ")" ::: "memory")
; #define PG8_BAR __builtin_amdgcn_s_barrier()
; #define PG8_SCHED __builtin_amdgcn_sched_barrier(0)
; template <class Epi, bool ALIGN_EPI>
; __device__ __forceinline__ void gemm_phase(LAS unsigned char* lds, const Gemm g, const StaticOrder& S, const Epi& E, const int wid) {
;     ...
;             PG8_LDB(B0, 1, 0); PG8_LDB(B1, 1, 1); PG8_SCHED; PG8_LDA(At, 1, 0); PG8_STAGE(PG8_SA(0, 1), a2 + hstep, voffA);
;             PG8_WAIT_V(8); PG8_WAIT_L(0); PG8_BAR; PG8_MMA(0, 0, At, B0); PG8_MMA(0, 1, At, B1); PG8_BAR; PG8_SCHED;
;             PG8_LDA(At, 1, 1); PG8_STAGE(PG8_SB(1, 0), b3, voffB); PG8_STAGE(PG8_SB(1, 1), b3 + hstepB, voffB); PG8_STAGE(PG8_SA(1, 0), a3, voffA);
;             PG8_WAIT_V(8); PG8_WAIT_L(0); PG8_BAR; PG8_MMA(1, 0, At, B0); PG8_MMA(1, 1, At, B1); PG8_BAR; PG8_SCHED;
;         }
	s_add_i32 s53, 0, 0x18000
	s_add_i32 s54, 0, 0x1c000
	v_add_u32_e32 v140, s53, v201
	v_add_u32_e32 v156, s54, v201
	ds_read_b128 v[128:131], v140
	ds_read_b128 v[132:135], v140 offset:1024
	ds_read_b128 v[136:139], v140 offset:2048
	ds_read_b128 v[140:143], v140 offset:3072
	ds_read_b128 v[144:147], v156
	ds_read_b128 v[148:151], v156 offset:1024
	ds_read_b128 v[152:155], v156 offset:2048
	ds_read_b128 v[156:159], v156 offset:3072
	s_add_u32 s30, s30, 0x80000
	s_addc_u32 s31, s31, 0
	s_mov_b32 m0, s39
	ds_read_b128 v[160:163], v205 offset:32768
	ds_read_b128 v[164:167], v205 offset:33792
	ds_read_b128 v[168:171], v205 offset:34816
	ds_read_b128 v[172:175], v205 offset:35840
	ds_read_b128 v[188:191], v205 offset:36864
	ds_read_b128 v[192:195], v205 offset:37888
	ds_read_b128 v[196:199], v205 offset:38912
	ds_read_b128 v[206:209], v205 offset:39936
	s_nop 0
	global_load_lds_dwordx4 v176, s[30:31]
	s_mov_b32 m0, s40
	s_nop 0
	global_load_lds_dwordx4 v180, s[30:31]
	s_waitcnt vmcnt(8)
	s_waitcnt lgkmcnt(0)
	s_barrier
	s_setprio 1
	v_mfma_f32_16x16x32_bf16 v[124:127], v[128:131], v[160:163], v[124:127]
	v_mfma_f32_16x16x32_bf16 v[120:123], v[136:139], v[160:163], v[120:123]
	v_mfma_f32_16x16x32_bf16 v[108:111], v[128:131], v[168:171], v[108:111]
	v_mfma_f32_16x16x32_bf16 v[104:107], v[136:139], v[168:171], v[104:107]
	v_mfma_f32_16x16x32_bf16 v[92:95], v[128:131], v[188:191], v[92:95]
	v_mfma_f32_16x16x32_bf16 v[88:91], v[136:139], v[188:191], v[88:91]
	v_mfma_f32_16x16x32_bf16 v[76:79], v[128:131], v[196:199], v[76:79]
	v_mfma_f32_16x16x32_bf16 v[72:75], v[136:139], v[196:199], v[72:75]
	v_mfma_f32_16x16x32_bf16 v[124:127], v[132:135], v[164:167], v[124:127]
	v_mfma_f32_16x16x32_bf16 v[120:123], v[140:143], v[164:167], v[120:123]
	v_mfma_f32_16x16x32_bf16 v[108:111], v[132:135], v[172:175], v[108:111]
	v_mfma_f32_16x16x32_bf16 v[104:107], v[140:143], v[172:175], v[104:107]
	v_mfma_f32_16x16x32_bf16 v[92:95], v[132:135], v[192:195], v[92:95]
	v_mfma_f32_16x16x32_bf16 v[88:91], v[140:143], v[192:195], v[88:91]
	v_mfma_f32_16x16x32_bf16 v[76:79], v[132:135], v[206:209], v[76:79]
	v_mfma_f32_16x16x32_bf16 v[72:75], v[140:143], v[206:209], v[72:75]
	v_mfma_f32_16x16x32_bf16 v[116:119], v[144:147], v[160:163], v[116:119]
	v_mfma_f32_16x16x32_bf16 v[112:115], v[152:155], v[160:163], v[112:115]
	v_mfma_f32_16x16x32_bf16 v[100:103], v[144:147], v[168:171], v[100:103]
	v_mfma_f32_16x16x32_bf16 v[96:99], v[152:155], v[168:171], v[96:99]
	v_mfma_f32_16x16x32_bf16 v[84:87], v[144:147], v[188:191], v[84:87]
	v_mfma_f32_16x16x32_bf16 v[80:83], v[152:155], v[188:191], v[80:83]
	v_mfma_f32_16x16x32_bf16 v[68:71], v[144:147], v[196:199], v[68:71]
	v_mfma_f32_16x16x32_bf16 v[64:67], v[152:155], v[196:199], v[64:67]
	v_mfma_f32_16x16x32_bf16 v[116:119], v[148:151], v[164:167], v[116:119]
	v_mfma_f32_16x16x32_bf16 v[112:115], v[156:159], v[164:167], v[112:115]
	v_mfma_f32_16x16x32_bf16 v[100:103], v[148:151], v[172:175], v[100:103]
	v_mfma_f32_16x16x32_bf16 v[96:99], v[156:159], v[172:175], v[96:99]
	v_mfma_f32_16x16x32_bf16 v[84:87], v[148:151], v[192:195], v[84:87]
	v_mfma_f32_16x16x32_bf16 v[80:83], v[156:159], v[192:195], v[80:83]
	v_mfma_f32_16x16x32_bf16 v[68:71], v[148:151], v[206:209], v[68:71]
	v_mfma_f32_16x16x32_bf16 v[64:67], v[156:159], v[206:209], v[64:67]
	s_setprio 0
	s_barrier
	s_add_u32 s30, s28, 0x80
	s_addc_u32 s31, s29, 0
	s_add_i32 s53, s53, s33
	ds_read_b128 v[160:163], v205 offset:49152
	ds_read_b128 v[164:167], v205 offset:50176
	ds_read_b128 v[168:171], v205 offset:51200
	ds_read_b128 v[172:175], v205 offset:52224
	ds_read_b128 v[188:191], v205 offset:53248
	ds_read_b128 v[192:195], v205 offset:54272
	ds_read_b128 v[196:199], v205 offset:55296
	ds_read_b128 v[206:209], v205 offset:56320
	s_mov_b32 m0, s53
	s_nop 0
	global_load_lds_dwordx4 v178, s[30:31]
	s_add_i32 m0, s53, 0x2000
	s_add_u32 s28, s28, 0x20080
	s_addc_u32 s29, s29, 0
	global_load_lds_dwordx4 v182, s[30:31]
	s_add_i32 s30, s54, s33
	s_mov_b32 m0, s30
	s_nop 0
	global_load_lds_dwordx4 v178, s[28:29]
	s_add_i32 m0, s30, 0x2000
	s_nop 0
	global_load_lds_dwordx4 v182, s[28:29]
	s_mov_b32 m0, s42
	s_nop 0
	global_load_lds_dwordx4 v176, s[26:27]
	s_mov_b32 m0, s43
	s_nop 0
	global_load_lds_dwordx4 v180, s[26:27]
	s_waitcnt vmcnt(8)
	s_waitcnt lgkmcnt(0)
	s_barrier
	s_setprio 1
	v_mfma_f32_16x16x32_bf16 v[60:63], v[128:131], v[160:163], v[60:63]
	v_mfma_f32_16x16x32_bf16 v[56:59], v[136:139], v[160:163], v[56:59]
	v_mfma_f32_16x16x32_bf16 v[44:47], v[128:131], v[168:171], v[44:47]
	v_mfma_f32_16x16x32_bf16 v[40:43], v[136:139], v[168:171], v[40:43]
	v_mfma_f32_16x16x32_bf16 v[28:31], v[128:131], v[188:191], v[28:31]
	v_mfma_f32_16x16x32_bf16 v[24:27], v[136:139], v[188:191], v[24:27]
	v_mfma_f32_16x16x32_bf16 v[12:15], v[128:131], v[196:199], v[12:15]
	v_mfma_f32_16x16x32_bf16 v[8:11], v[136:139], v[196:199], v[8:11]
	v_mfma_f32_16x16x32_bf16 v[60:63], v[132:135], v[164:167], v[60:63]
	v_mfma_f32_16x16x32_bf16 v[56:59], v[140:143], v[164:167], v[56:59]
	v_mfma_f32_16x16x32_bf16 v[44:47], v[132:135], v[172:175], v[44:47]
	v_mfma_f32_16x16x32_bf16 v[40:43], v[140:143], v[172:175], v[40:43]
	v_mfma_f32_16x16x32_bf16 v[28:31], v[132:135], v[192:195], v[28:31]
	v_mfma_f32_16x16x32_bf16 v[24:27], v[140:143], v[192:195], v[24:27]
	v_mfma_f32_16x16x32_bf16 v[12:15], v[132:135], v[206:209], v[12:15]
	v_mfma_f32_16x16x32_bf16 v[8:11], v[140:143], v[206:209], v[8:11]
	v_mfma_f32_16x16x32_bf16 v[52:55], v[144:147], v[160:163], v[52:55]
	v_mfma_f32_16x16x32_bf16 v[48:51], v[152:155], v[160:163], v[48:51]
	v_mfma_f32_16x16x32_bf16 v[36:39], v[144:147], v[168:171], v[36:39]
	v_mfma_f32_16x16x32_bf16 v[32:35], v[152:155], v[168:171], v[32:35]
	v_mfma_f32_16x16x32_bf16 v[20:23], v[144:147], v[188:191], v[20:23]
	v_mfma_f32_16x16x32_bf16 v[16:19], v[152:155], v[188:191], v[16:19]
	v_mfma_f32_16x16x32_bf16 v[4:7], v[144:147], v[196:199], v[4:7]
	v_mfma_f32_16x16x32_bf16 v[0:3], v[152:155], v[196:199], v[0:3]
	v_mfma_f32_16x16x32_bf16 v[52:55], v[148:151], v[164:167], v[52:55]
	v_mfma_f32_16x16x32_bf16 v[48:51], v[156:159], v[164:167], v[48:51]
	v_mfma_f32_16x16x32_bf16 v[36:39], v[148:151], v[172:175], v[36:39]
	v_mfma_f32_16x16x32_bf16 v[32:35], v[156:159], v[172:175], v[32:35]
	v_mfma_f32_16x16x32_bf16 v[20:23], v[148:151], v[192:195], v[20:23]
	v_mfma_f32_16x16x32_bf16 v[16:19], v[156:159], v[192:195], v[16:19]
	v_mfma_f32_16x16x32_bf16 v[4:7], v[148:151], v[206:209], v[4:7]
	v_mfma_f32_16x16x32_bf16 v[0:3], v[156:159], v[206:209], v[0:3]
	s_setprio 0
	s_barrier
	s_add_i32 s52, s52, 2
	s_add_u32 s48, s48, 0x100
	s_addc_u32 s49, s49, 0
	s_add_u32 s24, s24, 0x100
	s_addc_u32 s25, s25, 0
	s_add_u32 s50, s50, 0x100
	s_addc_u32 s51, s51, 0
	s_cmp_gt_u32 s52, 29
	s_cbranch_scc0 .LBB0_722
	s_and_b64 vcc, exec, s[84:85]
	s_cbranch_vccz .LBB0_725
	s_barrier

; #define PG8_STAGE(bufoff, gbase, voff) do { unsigned long long _gb = (unsigned long long)(gbase); asm volatile("" : "+s"(_gb)); _Pragma("unroll") for (int _i = 0; _i < 2; ++_i) \
;         __builtin_amdgcn_global_load_lds((const GAS unsigned*)((const GAS char*)_gb + (voff)[_i]), (LAS unsigned*)(lds + (bufoff) + ldsw + _i * 8192), 16, 0, 0); } while (0)
; #define PG8_LDA(dst, b, h) do { _Pragma("unroll") for (int m = 0; m < 4; ++m) _Pragma("unroll") for (int k = 0; k < 2; ++k) dst[m][k] = *(const LAS bf16x8*)(lds + PG8_SA(b, h) + aoff + m * 2048 + k * 1024); } while (0)
; #define PG8_LDB(dst, b, h) do { _Pragma("unroll") for (int n = 0; n < 2; ++n) _Pragma("unroll") for (int k = 0; k < 2; ++k) dst[n][k] = *(const LAS bf16x8*)(lds + PG8_SB(b, h) + boff + n * 2048 + k * 1024); } while (0)
; #define PG8_MMA(ai, bj, At, Bt) do { __builtin_amdgcn_s_setprio(1); _Pragma("unroll") for (int m = 0; m < 4; ++m) _Pragma("unroll") for (int n = 0; n < 2; ++n) _Pragma("unroll") for (int k = 0; k < 2; ++k) \
;         acc[ai][bj][m][n] = __builtin_amdgcn_mfma_f32_16x16x32_bf16(Bt[n][k], At[m][k], acc[ai][bj][m][n], 0, 0, 0); __builtin_amdgcn_s_setprio(0); } while (0)
; #define PG8_WAIT_V(n) asm volatile("s_waitcnt vmcnt(" #n ")" ::: "memory")
; #define PG8_WAIT_L(n) asm volatile("s_waitcnt lgkmcnt(" #n ")" ::: "memory")
; #define PG8_BAR __builtin_amdgcn_s_barrier()
; template <class Epi, bool ALIGN_EPI>
; __device__ __forceinline__ void gemm_phase(LAS unsigned char* lds, const Gemm g, const StaticOrder& S, const Epi& E, const int wid) {
;     ...
;             const bool last = (t == nt - 2);
;             const char* a1 = cA + (size_t)(t + 1) * kstep;
;             const char* a2 = last ? nA : cA + (size_t)(t + 2) * kstep; const char* b2 = last ? nB : cB + (size_t)(t + 2) * kstep;
;             const char* a3 = a2 + kstep; const char* b3 = b2 + kstep;
;             PG8_LDB(B0, 0, 0); PG8_LDB(B1, 0, 1); PG8_SCHED; PG8_LDA(At, 0, 0); PG8_STAGE(PG8_SA(1, 1), a1 + hstep, voffA);
;             PG8_WAIT_V(8); PG8_WAIT_L(0); PG8_BAR; PG8_MMA(0, 0, At, B0); PG8_MMA(0, 1, At, B1); PG8_BAR; PG8_SCHED;
;             PG8_LDA(At, 0, 1); PG8_STAGE(PG8_SB(0, 0), b2, voffB); PG8_STAGE(PG8_SB(0, 1), b2 + hstepB, voffB); PG8_STAGE(PG8_SA(0, 0), a2, voffA);
;             PG8_WAIT_V(8); PG8_WAIT_L(0); PG8_BAR; PG8_MMA(1, 0, At, B0); PG8_MMA(1, 1, At, B1); PG8_BAR; PG8_SCHED;
.LBB0_811:
	ds_read_b128 v[128:131], v202
	ds_read_b128 v[132:135], v202 offset:1024
	ds_read_b128 v[136:139], v202 offset:2048
	ds_read_b128 v[140:143], v202 offset:3072
	ds_read_b128 v[144:147], v203
	ds_read_b128 v[148:151], v203 offset:1024
	ds_read_b128 v[152:155], v203 offset:2048
	ds_read_b128 v[156:159], v203 offset:3072
	s_cmp_eq_u32 s49, 28
	s_cselect_b32 s24, s43, s47
	s_cselect_b32 s25, s13, s48
	s_cselect_b32 s22, s44, s45
	s_cselect_b32 s23, s11, s46
	s_add_u32 s20, s24, 0x80
	s_addc_u32 s21, s25, 0
	s_mov_b64 s[50:51], s[18:19]
	ds_read_b128 v[160:163], v204
	ds_read_b128 v[164:167], v204 offset:1024
	ds_read_b128 v[168:171], v204 offset:2048
	ds_read_b128 v[172:175], v204 offset:3072
	ds_read_b128 v[188:191], v204 offset:4096
	ds_read_b128 v[192:195], v204 offset:5120
	ds_read_b128 v[196:199], v204 offset:6144
	ds_read_b128 v[206:209], v204 offset:7168
	s_add_i32 m0, s28, 0xc000
	s_nop 0
	global_load_lds_dwordx4 v182, s[50:51]
	s_add_i32 m0, s28, 0xe000
	s_nop 0
	global_load_lds_dwordx4 v178, s[50:51]
	s_waitcnt vmcnt(8)
	s_waitcnt lgkmcnt(0)
	s_barrier
	s_setprio 1
	v_mfma_f32_16x16x32_bf16 v[124:127], v[128:131], v[160:163], v[124:127]
	v_mfma_f32_16x16x32_bf16 v[120:123], v[136:139], v[160:163], v[120:123]
	v_mfma_f32_16x16x32_bf16 v[108:111], v[128:131], v[168:171], v[108:111]
	v_mfma_f32_16x16x32_bf16 v[104:107], v[136:139], v[168:171], v[104:107]
	v_mfma_f32_16x16x32_bf16 v[92:95], v[128:131], v[188:191], v[92:95]
	v_mfma_f32_16x16x32_bf16 v[88:91], v[136:139], v[188:191], v[88:91]
	v_mfma_f32_16x16x32_bf16 v[76:79], v[128:131], v[196:199], v[76:79]
	v_mfma_f32_16x16x32_bf16 v[72:75], v[136:139], v[196:199], v[72:75]
	v_mfma_f32_16x16x32_bf16 v[124:127], v[132:135], v[164:167], v[124:127]
	v_mfma_f32_16x16x32_bf16 v[120:123], v[140:143], v[164:167], v[120:123]
	v_mfma_f32_16x16x32_bf16 v[108:111], v[132:135], v[172:175], v[108:111]
	v_mfma_f32_16x16x32_bf16 v[104:107], v[140:143], v[172:175], v[104:107]
	v_mfma_f32_16x16x32_bf16 v[92:95], v[132:135], v[192:195], v[92:95]
	v_mfma_f32_16x16x32_bf16 v[88:91], v[140:143], v[192:195], v[88:91]
	v_mfma_f32_16x16x32_bf16 v[76:79], v[132:135], v[206:209], v[76:79]
	v_mfma_f32_16x16x32_bf16 v[72:75], v[140:143], v[206:209], v[72:75]
	v_mfma_f32_16x16x32_bf16 v[116:119], v[144:147], v[160:163], v[116:119]
	v_mfma_f32_16x16x32_bf16 v[112:115], v[152:155], v[160:163], v[112:115]
	v_mfma_f32_16x16x32_bf16 v[100:103], v[144:147], v[168:171], v[100:103]
	v_mfma_f32_16x16x32_bf16 v[96:99], v[152:155], v[168:171], v[96:99]
	v_mfma_f32_16x16x32_bf16 v[84:87], v[144:147], v[188:191], v[84:87]
	v_mfma_f32_16x16x32_bf16 v[80:83], v[152:155], v[188:191], v[80:83]
	v_mfma_f32_16x16x32_bf16 v[68:71], v[144:147], v[196:199], v[68:71]
	v_mfma_f32_16x16x32_bf16 v[64:67], v[152:155], v[196:199], v[64:67]
	v_mfma_f32_16x16x32_bf16 v[116:119], v[148:151], v[164:167], v[116:119]
	v_mfma_f32_16x16x32_bf16 v[112:115], v[156:159], v[164:167], v[112:115]
	v_mfma_f32_16x16x32_bf16 v[100:103], v[148:151], v[172:175], v[100:103]
	v_mfma_f32_16x16x32_bf16 v[96:99], v[156:159], v[172:175], v[96:99]
	v_mfma_f32_16x16x32_bf16 v[84:87], v[148:151], v[192:195], v[84:87]
	v_mfma_f32_16x16x32_bf16 v[80:83], v[156:159], v[192:195], v[80:83]
	v_mfma_f32_16x16x32_bf16 v[68:71], v[148:151], v[206:209], v[68:71]
	v_mfma_f32_16x16x32_bf16 v[64:67], v[156:159], v[206:209], v[64:67]
	s_setprio 0
	s_barrier
	s_mov_b64 s[50:51], s[22:23]
	s_add_i32 s52, s38, s33
	ds_read_b128 v[160:163], v204 offset:16384
	ds_read_b128 v[164:167], v204 offset:17408
	ds_read_b128 v[168:171], v204 offset:18432
	ds_read_b128 v[172:175], v204 offset:19456
	ds_read_b128 v[188:191], v204 offset:20480
	ds_read_b128 v[192:195], v204 offset:21504
	ds_read_b128 v[196:199], v204 offset:22528
	ds_read_b128 v[206:209], v204 offset:23552
	s_mov_b32 m0, s52
	s_nop 0
	global_load_lds_dwordx4 v180, s[50:51]
	s_add_i32 m0, s52, 0x2000
	s_nop 0
	global_load_lds_dwordx4 v176, s[50:51]
	s_add_u32 s50, s22, 0x20000
	s_addc_u32 s51, s23, 0
	s_add_i32 s52, s39, s33
	s_mov_b32 m0, s52
	s_nop 0
	global_load_lds_dwordx4 v180, s[50:51]
	s_add_i32 m0, s52, 0x2000
	s_nop 0
	global_load_lds_dwordx4 v176, s[50:51]
	s_mov_b64 s[50:51], s[24:25]
	s_mov_b32 m0, s28
	s_nop 0
	global_load_lds_dwordx4 v182, s[50:51]
	s_mov_b32 m0, s29
	s_nop 0
	global_load_lds_dwordx4 v178, s[50:51]
	s_waitcnt vmcnt(8)
	s_waitcnt lgkmcnt(0)
	s_barrier
	s_setprio 1
	v_mfma_f32_16x16x32_bf16 v[60:63], v[128:131], v[160:163], v[60:63]
	v_mfma_f32_16x16x32_bf16 v[56:59], v[136:139], v[160:163], v[56:59]
	v_mfma_f32_16x16x32_bf16 v[44:47], v[128:131], v[168:171], v[44:47]
	v_mfma_f32_16x16x32_bf16 v[40:43], v[136:139], v[168:171], v[40:43]
	v_mfma_f32_16x16x32_bf16 v[28:31], v[128:131], v[188:191], v[28:31]
	v_mfma_f32_16x16x32_bf16 v[24:27], v[136:139], v[188:191], v[24:27]
	v_mfma_f32_16x16x32_bf16 v[12:15], v[128:131], v[196:199], v[12:15]
	v_mfma_f32_16x16x32_bf16 v[8:11], v[136:139], v[196:199], v[8:11]
	v_mfma_f32_16x16x32_bf16 v[60:63], v[132:135], v[164:167], v[60:63]
	v_mfma_f32_16x16x32_bf16 v[56:59], v[140:143], v[164:167], v[56:59]
	v_mfma_f32_16x16x32_bf16 v[44:47], v[132:135], v[172:175], v[44:47]
	v_mfma_f32_16x16x32_bf16 v[40:43], v[140:143], v[172:175], v[40:43]
	v_mfma_f32_16x16x32_bf16 v[28:31], v[132:135], v[192:195], v[28:31]
	v_mfma_f32_16x16x32_bf16 v[24:27], v[140:143], v[192:195], v[24:27]
	v_mfma_f32_16x16x32_bf16 v[12:15], v[132:135], v[206:209], v[12:15]
	v_mfma_f32_16x16x32_bf16 v[8:11], v[140:143], v[206:209], v[8:11]
	v_mfma_f32_16x16x32_bf16 v[52:55], v[144:147], v[160:163], v[52:55]
	v_mfma_f32_16x16x32_bf16 v[48:51], v[152:155], v[160:163], v[48:51]
	v_mfma_f32_16x16x32_bf16 v[36:39], v[144:147], v[168:171], v[36:39]
	v_mfma_f32_16x16x32_bf16 v[32:35], v[152:155], v[168:171], v[32:35]
	v_mfma_f32_16x16x32_bf16 v[20:23], v[144:147], v[188:191], v[20:23]
	v_mfma_f32_16x16x32_bf16 v[16:19], v[152:155], v[188:191], v[16:19]
	v_mfma_f32_16x16x32_bf16 v[4:7], v[144:147], v[196:199], v[4:7]
	v_mfma_f32_16x16x32_bf16 v[0:3], v[152:155], v[196:199], v[0:3]
	v_mfma_f32_16x16x32_bf16 v[52:55], v[148:151], v[164:167], v[52:55]
	v_mfma_f32_16x16x32_bf16 v[48:51], v[156:159], v[164:167], v[48:51]
	v_mfma_f32_16x16x32_bf16 v[36:39], v[148:151], v[172:175], v[36:39]
	v_mfma_f32_16x16x32_bf16 v[32:35], v[156:159], v[172:175], v[32:35]
	v_mfma_f32_16x16x32_bf16 v[20:23], v[148:151], v[192:195], v[20:23]
	v_mfma_f32_16x16x32_bf16 v[16:19], v[156:159], v[192:195], v[16:19]
	v_mfma_f32_16x16x32_bf16 v[4:7], v[148:151], v[206:209], v[4:7]
	v_mfma_f32_16x16x32_bf16 v[0:3], v[156:159], v[206:209], v[0:3]
	s_setprio 0
	s_barrier
; #define PG8_STAGE(bufoff, gbase, voff) do { unsigned long long _gb = (unsigned long long)(gbase); asm volatile("" : "+s"(_gb)); _Pragma("unroll") for (int _i = 0; _i < 2; ++_i) \
;         __builtin_amdgcn_global_load_lds((const GAS unsigned*)((const GAS char*)_gb + (voff)[_i]), (LAS unsigned*)(lds + (bufoff) + ldsw + _i * 8192), 16, 0, 0); } while (0)
; #define PG8_LDA(dst, b, h) do { _Pragma("unroll") for (int m = 0; m < 4; ++m) _Pragma("unroll") for (int k = 0; k < 2; ++k) dst[m][k] = *(const LAS bf16x8*)(lds + PG8_SA(b, h) + aoff + m * 2048 + k * 1024); } while (0)
; #define PG8_LDB(dst, b, h) do { _Pragma("unroll") for (int n = 0; n < 2; ++n) _Pragma("unroll") for (int k = 0; k < 2; ++k) dst[n][k] = *(const LAS bf16x8*)(lds + PG8_SB(b, h) + boff + n * 2048 + k * 1024); } while (0)
; #define PG8_MMA(ai, bj, At, Bt) do { __builtin_amdgcn_s_setprio(1); _Pragma("unroll") for (int m = 0; m < 4; ++m) _Pragma("unroll") for (int n = 0; n < 2; ++n) _Pragma("unroll") for (int k = 0; k < 2; ++k) \
;         acc[ai][bj][m][n] = __builtin_amdgcn_mfma_f32_16x16x32_bf16(Bt[n][k], At[m][k], acc[ai][bj][m][n], 0, 0, 0); __builtin_amdgcn_s_setprio(0); } while (0)
; #define PG8_WAIT_V(n) asm volatile("s_waitcnt vmcnt(" #n ")" ::: "memory")
; #define PG8_WAIT_L(n) asm volatile("s_waitcnt lgkmcnt(" #n ")" ::: "memory")
; #define PG8_BAR __builtin_amdgcn_s_barrier()
; #define PG8_SCHED __builtin_amdgcn_sched_barrier(0)
; template <class Epi, bool ALIGN_EPI>
; __device__ __forceinline__ void gemm_phase(LAS unsigned char* lds, const Gemm g, const StaticOrder& S, const Epi& E, const int wid) {
;     ...
;             PG8_LDB(B0, 1, 0); PG8_LDB(B1, 1, 1); PG8_SCHED; PG8_LDA(At, 1, 0); PG8_STAGE(PG8_SA(0, 1), a2 + hstep, voffA);
;             PG8_WAIT_V(8); PG8_WAIT_L(0); PG8_BAR; PG8_MMA(0, 0, At, B0); PG8_MMA(0, 1, At, B1); PG8_BAR; PG8_SCHED;
;             PG8_LDA(At, 1, 1); PG8_STAGE(PG8_SB(1, 0), b3, voffB); PG8_STAGE(PG8_SB(1, 1), b3 + hstepB, voffB); PG8_STAGE(PG8_SA(1, 0), a3, voffA);
;             PG8_WAIT_V(8); PG8_WAIT_L(0); PG8_BAR; PG8_MMA(1, 0, At, B0); PG8_MMA(1, 1, At, B1); PG8_BAR; PG8_SCHED;
;         }
	s_add_i32 s50, 0, 0x18000
	s_add_i32 s51, 0, 0x1c000
	v_add_u32_e32 v140, s50, v201
	v_add_u32_e32 v156, s51, v201
	ds_read_b128 v[128:131], v140
	ds_read_b128 v[132:135], v140 offset:1024
	ds_read_b128 v[136:139], v140 offset:2048
	ds_read_b128 v[140:143], v140 offset:3072
	ds_read_b128 v[144:147], v156
	ds_read_b128 v[148:151], v156 offset:1024
	ds_read_b128 v[152:155], v156 offset:2048
	ds_read_b128 v[156:159], v156 offset:3072
	s_add_u32 s24, s24, 0x80000
	s_addc_u32 s25, s25, 0
	s_mov_b32 m0, s30
	ds_read_b128 v[160:163], v204 offset:32768
	ds_read_b128 v[164:167], v204 offset:33792
	ds_read_b128 v[168:171], v204 offset:34816
	ds_read_b128 v[172:175], v204 offset:35840
	ds_read_b128 v[188:191], v204 offset:36864
	ds_read_b128 v[192:195], v204 offset:37888
	ds_read_b128 v[196:199], v204 offset:38912
	ds_read_b128 v[206:209], v204 offset:39936
	s_nop 0
	global_load_lds_dwordx4 v182, s[24:25]
	s_mov_b32 m0, s31
	s_nop 0
	global_load_lds_dwordx4 v178, s[24:25]
	s_waitcnt vmcnt(8)
	s_waitcnt lgkmcnt(0)
	s_barrier
	s_setprio 1
	v_mfma_f32_16x16x32_bf16 v[124:127], v[128:131], v[160:163], v[124:127]
	v_mfma_f32_16x16x32_bf16 v[120:123], v[136:139], v[160:163], v[120:123]
	v_mfma_f32_16x16x32_bf16 v[108:111], v[128:131], v[168:171], v[108:111]
	v_mfma_f32_16x16x32_bf16 v[104:107], v[136:139], v[168:171], v[104:107]
	v_mfma_f32_16x16x32_bf16 v[92:95], v[128:131], v[188:191], v[92:95]
	v_mfma_f32_16x16x32_bf16 v[88:91], v[136:139], v[188:191], v[88:91]
	v_mfma_f32_16x16x32_bf16 v[76:79], v[128:131], v[196:199], v[76:79]
	v_mfma_f32_16x16x32_bf16 v[72:75], v[136:139], v[196:199], v[72:75]
	v_mfma_f32_16x16x32_bf16 v[124:127], v[132:135], v[164:167], v[124:127]
	v_mfma_f32_16x16x32_bf16 v[120:123], v[140:143], v[164:167], v[120:123]
	v_mfma_f32_16x16x32_bf16 v[108:111], v[132:135], v[172:175], v[108:111]
	v_mfma_f32_16x16x32_bf16 v[104:107], v[140:143], v[172:175], v[104:107]
	v_mfma_f32_16x16x32_bf16 v[92:95], v[132:135], v[192:195], v[92:95]
	v_mfma_f32_16x16x32_bf16 v[88:91], v[140:143], v[192:195], v[88:91]
	v_mfma_f32_16x16x32_bf16 v[76:79], v[132:135], v[206:209], v[76:79]
	v_mfma_f32_16x16x32_bf16 v[72:75], v[140:143], v[206:209], v[72:75]
	v_mfma_f32_16x16x32_bf16 v[116:119], v[144:147], v[160:163], v[116:119]
	v_mfma_f32_16x16x32_bf16 v[112:115], v[152:155], v[160:163], v[112:115]
	v_mfma_f32_16x16x32_bf16 v[100:103], v[144:147], v[168:171], v[100:103]
	v_mfma_f32_16x16x32_bf16 v[96:99], v[152:155], v[168:171], v[96:99]
	v_mfma_f32_16x16x32_bf16 v[84:87], v[144:147], v[188:191], v[84:87]
	v_mfma_f32_16x16x32_bf16 v[80:83], v[152:155], v[188:191], v[80:83]
	v_mfma_f32_16x16x32_bf16 v[68:71], v[144:147], v[196:199], v[68:71]
	v_mfma_f32_16x16x32_bf16 v[64:67], v[152:155], v[196:199], v[64:67]
	v_mfma_f32_16x16x32_bf16 v[116:119], v[148:151], v[164:167], v[116:119]
	v_mfma_f32_16x16x32_bf16 v[112:115], v[156:159], v[164:167], v[112:115]
	v_mfma_f32_16x16x32_bf16 v[100:103], v[148:151], v[172:175], v[100:103]
	v_mfma_f32_16x16x32_bf16 v[96:99], v[156:159], v[172:175], v[96:99]
	v_mfma_f32_16x16x32_bf16 v[84:87], v[148:151], v[192:195], v[84:87]
	v_mfma_f32_16x16x32_bf16 v[80:83], v[156:159], v[192:195], v[80:83]
	v_mfma_f32_16x16x32_bf16 v[68:71], v[148:151], v[206:209], v[68:71]
	v_mfma_f32_16x16x32_bf16 v[64:67], v[156:159], v[206:209], v[64:67]
	s_setprio 0
	s_barrier
	s_add_u32 s24, s22, 0x80
	s_addc_u32 s25, s23, 0
	s_add_i32 s50, s50, s33
	ds_read_b128 v[160:163], v204 offset:49152
	ds_read_b128 v[164:167], v204 offset:50176
	ds_read_b128 v[168:171], v204 offset:51200
	ds_read_b128 v[172:175], v204 offset:52224
	ds_read_b128 v[188:191], v204 offset:53248
	ds_read_b128 v[192:195], v204 offset:54272
	ds_read_b128 v[196:199], v204 offset:55296
	ds_read_b128 v[206:209], v204 offset:56320
	s_mov_b32 m0, s50
	s_nop 0
	global_load_lds_dwordx4 v180, s[24:25]
	s_add_i32 m0, s50, 0x2000
	s_add_u32 s22, s22, 0x20080
	s_addc_u32 s23, s23, 0
	global_load_lds_dwordx4 v176, s[24:25]
	s_add_i32 s24, s51, s33
	s_mov_b32 m0, s24
	s_nop 0
	global_load_lds_dwordx4 v180, s[22:23]
	s_add_i32 m0, s24, 0x2000
	s_nop 0
	global_load_lds_dwordx4 v176, s[22:23]
	s_mov_b32 m0, s34
	s_nop 0
	global_load_lds_dwordx4 v182, s[20:21]
	s_mov_b32 m0, s35
	s_nop 0
	global_load_lds_dwordx4 v178, s[20:21]
	s_waitcnt vmcnt(8)
	s_waitcnt lgkmcnt(0)
	s_barrier
	s_setprio 1
	v_mfma_f32_16x16x32_bf16 v[60:63], v[128:131], v[160:163], v[60:63]
	v_mfma_f32_16x16x32_bf16 v[56:59], v[136:139], v[160:163], v[56:59]
	v_mfma_f32_16x16x32_bf16 v[44:47], v[128:131], v[168:171], v[44:47]
	v_mfma_f32_16x16x32_bf16 v[40:43], v[136:139], v[168:171], v[40:43]
	v_mfma_f32_16x16x32_bf16 v[28:31], v[128:131], v[188:191], v[28:31]
	v_mfma_f32_16x16x32_bf16 v[24:27], v[136:139], v[188:191], v[24:27]
	v_mfma_f32_16x16x32_bf16 v[12:15], v[128:131], v[196:199], v[12:15]
	v_mfma_f32_16x16x32_bf16 v[8:11], v[136:139], v[196:199], v[8:11]
	v_mfma_f32_16x16x32_bf16 v[60:63], v[132:135], v[164:167], v[60:63]
	v_mfma_f32_16x16x32_bf16 v[56:59], v[140:143], v[164:167], v[56:59]
	v_mfma_f32_16x16x32_bf16 v[44:47], v[132:135], v[172:175], v[44:47]
	v_mfma_f32_16x16x32_bf16 v[40:43], v[140:143], v[172:175], v[40:43]
	v_mfma_f32_16x16x32_bf16 v[28:31], v[132:135], v[192:195], v[28:31]
	v_mfma_f32_16x16x32_bf16 v[24:27], v[140:143], v[192:195], v[24:27]
	v_mfma_f32_16x16x32_bf16 v[12:15], v[132:135], v[206:209], v[12:15]
	v_mfma_f32_16x16x32_bf16 v[8:11], v[140:143], v[206:209], v[8:11]
	v_mfma_f32_16x16x32_bf16 v[52:55], v[144:147], v[160:163], v[52:55]
	v_mfma_f32_16x16x32_bf16 v[48:51], v[152:155], v[160:163], v[48:51]
	v_mfma_f32_16x16x32_bf16 v[36:39], v[144:147], v[168:171], v[36:39]
	v_mfma_f32_16x16x32_bf16 v[32:35], v[152:155], v[168:171], v[32:35]
	v_mfma_f32_16x16x32_bf16 v[20:23], v[144:147], v[188:191], v[20:23]
	v_mfma_f32_16x16x32_bf16 v[16:19], v[152:155], v[188:191], v[16:19]
	v_mfma_f32_16x16x32_bf16 v[4:7], v[144:147], v[196:199], v[4:7]
	v_mfma_f32_16x16x32_bf16 v[0:3], v[152:155], v[196:199], v[0:3]
	v_mfma_f32_16x16x32_bf16 v[52:55], v[148:151], v[164:167], v[52:55]
	v_mfma_f32_16x16x32_bf16 v[48:51], v[156:159], v[164:167], v[48:51]
	v_mfma_f32_16x16x32_bf16 v[36:39], v[148:151], v[172:175], v[36:39]
	v_mfma_f32_16x16x32_bf16 v[32:35], v[156:159], v[172:175], v[32:35]
	v_mfma_f32_16x16x32_bf16 v[20:23], v[148:151], v[192:195], v[20:23]
	v_mfma_f32_16x16x32_bf16 v[16:19], v[156:159], v[192:195], v[16:19]
	v_mfma_f32_16x16x32_bf16 v[4:7], v[148:151], v[206:209], v[4:7]
	v_mfma_f32_16x16x32_bf16 v[0:3], v[156:159], v[206:209], v[0:3]
	s_setprio 0
	s_barrier
	s_add_i32 s49, s49, 2
	s_add_u32 s45, s45, 0x100
	s_addc_u32 s46, s46, 0
	s_add_u32 s18, s18, 0x100
	s_addc_u32 s19, s19, 0
	s_add_u32 s47, s47, 0x100
	s_addc_u32 s48, s48, 0
	s_cmp_gt_u32 s49, 29
	s_cbranch_scc0 .LBB0_811
	s_and_b64 vcc, exec, s[84:85]
	s_cbranch_vccz .LBB0_814
	s_barrier
